# norm3 ctx-row split-K reduce: hoist all partial+gate loads to loop top (1 round trip instead of 8)
# speedup vs baseline: 1.0101x; 1.0015x over previous
; __device__ __forceinline__ void norm_phase(const float* xL, const float* xC, const float* gain, const float* modl  , int ishift, bf16_t* H, int nrows,
;                                            const float* part, int nsplit, const float* pgate  , float pscale, float* xCw) {
;     ...
;     if (nsplit > 0) for (int row = RL + gw; row < nrows; row += NGW) {
;         f32x4 v[4];
;         const float* xr = xC + (size_t)(row - RL) * DM;
; #pragma unroll
;         for (int j = 0; j < 4; ++j) v[j] = *(const f32x4*)(xr + 4 * lane + 256 * j);
; #pragma unroll
;         for (int j = 0; j < 4; ++j) {
;             f32x4 pv[11];
; #pragma unroll
;             for (int ks = 0; ks < 11; ++ks) if (ks < nsplit) pv[ks] = *(const f32x4*)(part + ((size_t)ks * RC + (row - RL)) * DM + 4 * lane + 256 * j);
;             f32x4 sum = {0.f, 0.f, 0.f, 0.f};
; #pragma unroll
;             for (int ks = 0; ks < 11; ++ks) if (ks < nsplit) sum += pv[ks];
;             v[j] += sum * (*(const f32x4*)(pgate + 4 * lane + 256 * j) * pscale);
;             *(f32x4*)(xCw + (size_t)(row - RL) * DM + 4 * lane + 256 * j) = v[j];
.LBB0_1004:
	v_lshl_add_u64 v[40:41], s[96:97], 0, v[72:73]
	v_add_co_u32_e32 v32, vcc, 0x12000000, v40
	s_add_i32 s0, s0, s88
	s_nop 0
	v_addc_co_u32_e32 v33, vcc, 0, v41, vcc
	v_add_co_u32_e32 v34, vcc, 0x21b80000, v40
	global_load_dwordx4 v[16:19], v[32:33], off
	global_load_dwordx4 v[24:27], v[32:33], off offset:1024
	global_load_dwordx4 v[28:31], v[32:33], off offset:2048
	global_load_dwordx4 v[20:23], v[32:33], off offset:3072
	v_addc_co_u32_e32 v35, vcc, 0, v41, vcc
	v_add_co_u32_e32 v36, vcc, 0x21f80000, v40
	global_load_dwordx4 v[42:45], v[34:35], off
	s_nop 0
	v_addc_co_u32_e32 v37, vcc, 0, v41, vcc
	v_add_co_u32_e32 v38, vcc, 0x22380000, v40
	global_load_dwordx4 v[46:49], v[36:37], off
	s_nop 0
	v_addc_co_u32_e32 v39, vcc, 0, v41, vcc
	v_add_co_u32_e32 v40, vcc, 0x22780000, v40
	global_load_dwordx4 v[50:53], v[38:39], off
	s_nop 0
	v_addc_co_u32_e32 v41, vcc, 0, v41, vcc
	global_load_dwordx4 v[54:57], v[40:41], off
	global_load_dwordx4 v[80:83], v[64:65], off
	global_load_dwordx4 v[84:87], v[64:65], off offset:1024
	global_load_dwordx4 v[88:91], v[64:65], off offset:2048
	global_load_dwordx4 v[92:95], v[64:65], off offset:3072
	global_load_dwordx4 v[96:99], v[34:35], off offset:1024
	global_load_dwordx4 v[100:103], v[36:37], off offset:1024
	global_load_dwordx4 v[104:107], v[38:39], off offset:1024
	global_load_dwordx4 v[108:111], v[40:41], off offset:1024
	global_load_dwordx4 v[112:115], v[34:35], off offset:2048
	global_load_dwordx4 v[116:119], v[36:37], off offset:2048
	global_load_dwordx4 v[120:123], v[38:39], off offset:2048
	global_load_dwordx4 v[124:127], v[40:41], off offset:2048
	global_load_dwordx4 v[128:131], v[34:35], off offset:3072
	global_load_dwordx4 v[132:135], v[36:37], off offset:3072
	global_load_dwordx4 v[136:139], v[38:39], off offset:3072
	global_load_dwordx4 v[140:143], v[40:41], off offset:3072
	v_lshl_add_u64 v[72:73], v[72:73], 0, s[64:65]
	s_cmp_lt_i32 s0, s5
	s_waitcnt vmcnt(19)
	v_add_f32_e32 v44, 0, v44
	v_add_f32_e32 v45, 0, v45
	v_add_f32_e32 v42, 0, v42
	v_add_f32_e32 v43, 0, v43
	s_waitcnt vmcnt(18)
	v_add_f32_e32 v44, v44, v48
	v_add_f32_e32 v45, v45, v49
	v_add_f32_e32 v42, v42, v46
	v_add_f32_e32 v43, v43, v47
	s_waitcnt vmcnt(17)
	v_add_f32_e32 v44, v44, v52
	v_add_f32_e32 v45, v45, v53
	v_add_f32_e32 v42, v42, v50
	v_add_f32_e32 v43, v43, v51
	s_waitcnt vmcnt(16)
	v_add_f32_e32 v46, v44, v56
	v_add_f32_e32 v47, v45, v57
	v_add_f32_e32 v48, v42, v54
	v_add_f32_e32 v49, v43, v55
	s_waitcnt vmcnt(15)
	v_fma_f32 v18, v46, v82, v18
	v_fma_f32 v19, v47, v83, v19
	v_fma_f32 v16, v48, v80, v16
	v_fma_f32 v17, v49, v81, v17
	global_store_dwordx4 v[32:33], v[16:19], off
	v_mul_f32_e32 v74, v17, v17
	v_mul_f32_e32 v75, v19, v19
	v_fmac_f32_e32 v74, v16, v16
	v_fmac_f32_e32 v75, v18, v18
	v_add_f32_e32 v74, v74, v75
	s_waitcnt vmcnt(12)
	v_add_f32_e32 v44, 0, v98
	v_add_f32_e32 v45, 0, v99
	v_add_f32_e32 v42, 0, v96
	v_add_f32_e32 v43, 0, v97
	s_waitcnt vmcnt(11)
	v_add_f32_e32 v44, v44, v102
	v_add_f32_e32 v45, v45, v103
	v_add_f32_e32 v42, v42, v100
	v_add_f32_e32 v43, v43, v101
	s_waitcnt vmcnt(10)
	v_add_f32_e32 v44, v44, v106
	v_add_f32_e32 v45, v45, v107
	v_add_f32_e32 v42, v42, v104
	v_add_f32_e32 v43, v43, v105
	s_waitcnt vmcnt(9)
	v_add_f32_e32 v46, v44, v110
	v_add_f32_e32 v47, v45, v111
	v_add_f32_e32 v48, v42, v108
	v_add_f32_e32 v49, v43, v109
	v_fma_f32 v26, v46, v86, v26
	v_fma_f32 v27, v47, v87, v27
	v_fma_f32 v24, v48, v84, v24
	v_fma_f32 v25, v49, v85, v25
	global_store_dwordx4 v[32:33], v[24:27], off offset:1024
	v_mul_f32_e32 v75, v25, v25
	v_mul_f32_e32 v76, v27, v27
	v_fmac_f32_e32 v75, v24, v24
	v_fmac_f32_e32 v76, v26, v26
	v_add_f32_e32 v75, v75, v76
	v_add_f32_e32 v74, v74, v75
	s_waitcnt vmcnt(9)
	v_add_f32_e32 v44, 0, v114
	v_add_f32_e32 v45, 0, v115
	v_add_f32_e32 v42, 0, v112
	v_add_f32_e32 v43, 0, v113
	s_waitcnt vmcnt(8)
	v_add_f32_e32 v44, v44, v118
	v_add_f32_e32 v45, v45, v119
	v_add_f32_e32 v42, v42, v116
	v_add_f32_e32 v43, v43, v117
	s_waitcnt vmcnt(7)
	v_add_f32_e32 v44, v44, v122
	v_add_f32_e32 v45, v45, v123
	v_add_f32_e32 v42, v42, v120
	v_add_f32_e32 v43, v43, v121
	s_waitcnt vmcnt(6)
	v_add_f32_e32 v46, v44, v126
	v_add_f32_e32 v47, v45, v127
	v_add_f32_e32 v48, v42, v124
	v_add_f32_e32 v49, v43, v125
	v_fma_f32 v30, v46, v90, v30
	v_fma_f32 v31, v47, v91, v31
	v_fma_f32 v28, v48, v88, v28
	v_fma_f32 v29, v49, v89, v29
	global_store_dwordx4 v[32:33], v[28:31], off offset:2048
	v_mul_f32_e32 v75, v29, v29
	v_mul_f32_e32 v76, v31, v31
	v_fmac_f32_e32 v75, v28, v28
	v_fmac_f32_e32 v76, v30, v30
	v_add_f32_e32 v75, v75, v76
	v_add_f32_e32 v74, v74, v75
	s_waitcnt vmcnt(6)
; __device__ __forceinline__ unsigned cvt_pk_bf16(float lo, float hi) { const f32x2 v = {lo, hi}; const bf16x2_t b = __builtin_convertvector(v, bf16x2_t); return __builtin_bit_cast(unsigned, b); }
; __device__ __forceinline__ float wave_sum(float v) { return xadd32(sum32(v)); }
; __device__ __forceinline__ void norm_row(const f32x4 (&v)[4], const f32x4 (&gn)[4], const float* sh, bf16_t* hrow, int lane) {
;     const float* scl = sh + 1024;
;     f32x4 sv[4], cv[4];
; #pragma unroll
;     for (int j = 0; j < 4; ++j) { sv[j] = *(const f32x4*)(sh + 4 * lane + 256 * j); cv[j] = *(const f32x4*)(scl + 4 * lane + 256 * j); }
;     float ss = 0.f;
; #pragma unroll
;     for (int j = 0; j < 4; ++j) ss += (v[j][0] * v[j][0] + v[j][1] * v[j][1]) + (v[j][2] * v[j][2] + v[j][3] * v[j][3]);
;     const float rstd = __builtin_amdgcn_rsqf(wave_sum(ss) * (1.0f / DM) + EPS);
; #pragma unroll
;     for (int j = 0; j < 4; ++j) {
;         const f32x4 y = v[j] * rstd * gn[j] * (cv[j] + 1.0f) + sv[j];
;         u32x2 w; w.x = cvt_pk_bf16(y[0], y[1]); w.y = cvt_pk_bf16(y[2], y[3]);
;         *(u32x2*)(hrow + 4 * lane + 256 * j) = w;
;     }
; __device__ __forceinline__ void norm_phase(const float* xL, const float* xC, const float* gain, const float* modl  , int ishift, bf16_t* H, int nrows,
;                                            const float* part, int nsplit, const float* pgate  , float pscale, float* xCw) {
;     ...
;     if (nsplit > 0) for (int row = RL + gw; row < nrows; row += NGW) {
;         f32x4 v[4];
;         const float* xr = xC + (size_t)(row - RL) * DM;
; #pragma unroll
;         for (int j = 0; j < 4; ++j) v[j] = *(const f32x4*)(xr + 4 * lane + 256 * j);
; #pragma unroll
;         for (int j = 0; j < 4; ++j) {
;             f32x4 pv[11];
; #pragma unroll
;             for (int ks = 0; ks < 11; ++ks) if (ks < nsplit) pv[ks] = *(const f32x4*)(part + ((size_t)ks * RC + (row - RL)) * DM + 4 * lane + 256 * j);
;             f32x4 sum = {0.f, 0.f, 0.f, 0.f};
; #pragma unroll
;             for (int ks = 0; ks < 11; ++ks) if (ks < nsplit) sum += pv[ks];
;             v[j] += sum * (*(const f32x4*)(pgate + 4 * lane + 256 * j) * pscale);
;             *(f32x4*)(xCw + (size_t)(row - RL) * DM + 4 * lane + 256 * j) = v[j];
;         }
;         norm_row(v, gn, modl + (size_t)4 * 9216 + ishift * 1024, H + (size_t)row * DM, lane);
	v_add_f32_e32 v44, 0, v130
	v_add_f32_e32 v45, 0, v131
	v_add_f32_e32 v42, 0, v128
	v_add_f32_e32 v43, 0, v129
	s_waitcnt vmcnt(5)
	v_add_f32_e32 v44, v44, v134
	v_add_f32_e32 v45, v45, v135
	v_add_f32_e32 v42, v42, v132
	v_add_f32_e32 v43, v43, v133
	s_waitcnt vmcnt(4)
	v_add_f32_e32 v44, v44, v138
	v_add_f32_e32 v45, v45, v139
	v_add_f32_e32 v42, v42, v136
	v_add_f32_e32 v43, v43, v137
	s_waitcnt vmcnt(3)
	v_add_f32_e32 v46, v44, v142
	v_add_f32_e32 v47, v45, v143
	v_add_f32_e32 v48, v42, v140
	v_add_f32_e32 v49, v43, v141
	v_fma_f32 v22, v46, v94, v22
	v_fma_f32 v23, v47, v95, v23
	v_fma_f32 v20, v48, v92, v20
	v_fma_f32 v21, v49, v93, v21
	global_store_dwordx4 v[32:33], v[20:23], off offset:3072
	global_load_dwordx4 v[56:59], v[66:67], off
	global_load_dwordx4 v[60:63], v[68:69], off
	global_load_dwordx4 v[48:51], v[66:67], off offset:1024
	global_load_dwordx4 v[52:55], v[68:69], off offset:1024
	global_load_dwordx4 v[40:43], v[66:67], off offset:2048
	global_load_dwordx4 v[44:47], v[68:69], off offset:2048
	global_load_dwordx4 v[32:35], v[66:67], off offset:3072
	global_load_dwordx4 v[36:39], v[68:69], off offset:3072
	v_mul_f32_e32 v75, v21, v21
	v_mul_f32_e32 v76, v23, v23
	v_fmac_f32_e32 v75, v20, v20
	v_fmac_f32_e32 v76, v22, v22
	v_add_f32_e32 v75, v75, v76
	v_add_f32_e32 v74, v74, v75
	ds_swizzle_b32 v75, v74 offset:swizzle(SWAP,1)
	v_lshl_add_u64 v[76:77], s[96:97], 0, v[70:71]
	v_lshl_add_u64 v[70:71], v[70:71], 0, s[92:93]
	s_waitcnt lgkmcnt(0)
	v_add_f32_e32 v74, v74, v75
	ds_swizzle_b32 v75, v74 offset:swizzle(SWAP,2)
	s_waitcnt lgkmcnt(0)
	v_add_f32_e32 v74, v74, v75
	ds_swizzle_b32 v75, v74 offset:swizzle(SWAP,4)
	s_waitcnt lgkmcnt(0)
	v_add_f32_e32 v74, v74, v75
	ds_swizzle_b32 v75, v74 offset:swizzle(SWAP,8)
	s_waitcnt lgkmcnt(0)
	v_add_f32_e32 v74, v74, v75
	ds_swizzle_b32 v75, v74 offset:swizzle(SWAP,16)
	s_waitcnt lgkmcnt(0)
	v_add_f32_e32 v74, v74, v75
	v_mov_b32_e32 v75, v74
	s_nop 1
	v_permlane32_swap_b32_e32 v74, v75
	v_add_f32_e32 v74, v74, v75
	v_fmamk_f32 v74, v74, 0x3a800000, v193
	v_rsq_f32_e32 v74, v74
	s_waitcnt vmcnt(6)
	v_add_f32_e32 v62, 1.0, v62
	v_add_f32_e32 v63, 1.0, v63
	v_mul_f32_e32 v18, v18, v74
	v_mul_f32_e32 v19, v19, v74
	v_mul_f32_e32 v16, v16, v74
	v_mul_f32_e32 v17, v17, v74
	v_mul_f32_e32 v18, v2, v18
	v_mul_f32_e32 v19, v3, v19
	v_mul_f32_e32 v16, v0, v16
	v_mul_f32_e32 v17, v1, v17
	v_add_f32_e32 v60, 1.0, v60
	v_add_f32_e32 v61, 1.0, v61
	v_fma_f32 v18, v62, v18, v58
	v_fma_f32 v19, v63, v19, v59
	v_fma_f32 v16, v60, v16, v56
	v_fma_f32 v17, v61, v17, v57
	v_mul_f32_e32 v24, v24, v74
	v_mul_f32_e32 v25, v25, v74
	v_cvt_pk_bf16_f32 v16, v16, v17
	v_cvt_pk_bf16_f32 v17, v18, v19
	v_add_co_u32_e32 v18, vcc, s47, v76
	v_mul_f32_e32 v24, v4, v24
	v_mul_f32_e32 v25, v5, v25
	s_nop 0
	v_addc_co_u32_e32 v19, vcc, 0, v77, vcc
	global_store_dwordx2 v[18:19], v[16:17], off
	v_mul_f32_e32 v16, v26, v74
	v_mul_f32_e32 v17, v27, v74
	s_waitcnt vmcnt(5)
	v_add_f32_e32 v26, 1.0, v54
	v_add_f32_e32 v27, 1.0, v55
	v_mul_f32_e32 v16, v6, v16
	v_mul_f32_e32 v17, v7, v17
	v_add_f32_e32 v52, 1.0, v52
	v_add_f32_e32 v53, 1.0, v53
	v_fma_f32 v16, v26, v16, v50
	v_fma_f32 v17, v27, v17, v51
	v_fma_f32 v24, v52, v24, v48
	v_fma_f32 v25, v53, v25, v49
	s_waitcnt vmcnt(3)
	v_add_f32_e32 v26, 1.0, v46
	v_add_f32_e32 v27, 1.0, v47
	v_cvt_pk_bf16_f32 v24, v24, v25
	v_cvt_pk_bf16_f32 v25, v16, v17
	global_store_dwordx2 v[18:19], v[24:25], off offset:512
	v_mul_f32_e32 v16, v30, v74
	v_mul_f32_e32 v17, v31, v74
	v_mul_f32_e32 v24, v28, v74
	v_mul_f32_e32 v25, v29, v74
	v_mul_f32_e32 v16, v10, v16
	v_mul_f32_e32 v17, v11, v17
	v_mul_f32_e32 v24, v8, v24
	v_mul_f32_e32 v25, v9, v25
	v_add_f32_e32 v28, 1.0, v44
	v_add_f32_e32 v29, 1.0, v45
	v_fma_f32 v16, v26, v16, v42
	v_fma_f32 v17, v27, v17, v43
	v_fma_f32 v24, v28, v24, v40
	v_fma_f32 v25, v29, v25, v41
	v_mul_f32_e32 v20, v20, v74
	v_mul_f32_e32 v21, v21, v74
	v_cvt_pk_bf16_f32 v24, v24, v25
	v_cvt_pk_bf16_f32 v25, v16, v17
	v_mul_f32_e32 v16, v22, v74
	v_mul_f32_e32 v17, v23, v74
	global_store_dwordx2 v[18:19], v[24:25], off offset:1024
	v_mul_f32_e32 v20, v12, v20
	v_mul_f32_e32 v21, v13, v21
	v_mul_f32_e32 v16, v14, v16
	v_mul_f32_e32 v17, v15, v17
	s_waitcnt vmcnt(3)
	v_add_f32_e32 v22, 1.0, v38
	v_add_f32_e32 v23, 1.0, v39
	v_add_f32_e32 v24, 1.0, v36
	v_add_f32_e32 v25, 1.0, v37
	v_fma_f32 v16, v22, v16, v34
	v_fma_f32 v17, v23, v17, v35
	v_fma_f32 v20, v24, v20, v32
	v_fma_f32 v21, v25, v21, v33
	s_nop 0
	v_cvt_pk_bf16_f32 v20, v20, v21
	v_cvt_pk_bf16_f32 v21, v16, v17
	global_store_dwordx2 v[18:19], v[20:21], off offset:1536
	s_cbranch_scc1 .LBB0_1004
